# MLA attention: second key-half QK MFMAs deferred and interleaved with the first half's exp/sum VALU work (intra-wave MFMA/VALU overlap)
# baseline (speedup 1.0000x reference)
; template <int DQK, int NMAP, int DV> ...
;     ...
;       if (act0) ATTN_QK(sa0, kbase + c * DQK);
;       if (act1) ATTN_QK(sa1, kbase + 32 * KS + c * DQK);
.LBB0_1398:
	s_add_i32 s62, s19, 32
	s_cmp_le_i32 s62, s16
	s_cselect_b64 s[0:1], -1, 0
	s_cmp_gt_i32 s62, s16
	s_cbranch_scc1 .LBB0_1400
	s_mov_b32 s100, 0
	s_and_b64 vcc, exec, s[12:13]
	s_cbranch_vccz .Lmq1_orig
	s_mov_b32 s100, 1
	ds_read_b128 v[228:231], v219 offset:12800
	ds_read_b128 v[232:235], v219 offset:12832
	ds_read_b128 v[236:239], v219 offset:12864
	ds_read_b128 v[240:243], v219 offset:12896
	v_mov_b32_e32 v248, v219
	s_branch .LBB0_1401
.Lmq1_orig:
	ds_read_b128 v[2:5], v219 offset:12800
	ds_read_b128 v[6:9], v219 offset:12832
	ds_read_b128 v[10:13], v219 offset:12864
	ds_read_b128 v[220:223], v219 offset:12896
	s_waitcnt lgkmcnt(3)
	v_mfma_f32_32x32x16_bf16 v[80:95], v[2:5], v[156:159], 0
	ds_read_b128 v[224:227], v219 offset:12928
	s_waitcnt lgkmcnt(3)
	v_mfma_f32_32x32x16_bf16 v[80:95], v[6:9], v[152:155], v[80:95]
	ds_read_b128 v[2:5], v219 offset:12960
	s_waitcnt lgkmcnt(3)
	v_mfma_f32_32x32x16_bf16 v[80:95], v[10:13], v[148:151], v[80:95]
	ds_read_b128 v[6:9], v219 offset:12992
	s_waitcnt lgkmcnt(3)
	v_mfma_f32_32x32x16_bf16 v[80:95], v[220:223], v[144:147], v[80:95]
	ds_read_b128 v[10:13], v219 offset:13024
	s_waitcnt lgkmcnt(3)
	v_mfma_f32_32x32x16_bf16 v[80:95], v[224:227], v[140:143], v[80:95]
	ds_read_b128 v[220:223], v219 offset:13056
	s_waitcnt lgkmcnt(3)
	v_mfma_f32_32x32x16_bf16 v[80:95], v[2:5], v[136:139], v[80:95]
	ds_read_b128 v[224:227], v219 offset:13088
	s_waitcnt lgkmcnt(3)
	v_mfma_f32_32x32x16_bf16 v[80:95], v[6:9], v[132:135], v[80:95]
	ds_read_b128 v[2:5], v219 offset:13120
	s_waitcnt lgkmcnt(3)
	v_mfma_f32_32x32x16_bf16 v[80:95], v[10:13], v[128:131], v[80:95]
	ds_read_b128 v[6:9], v219 offset:13152
	s_waitcnt lgkmcnt(3)
	v_mfma_f32_32x32x16_bf16 v[80:95], v[220:223], v[124:127], v[80:95]
	s_waitcnt lgkmcnt(2)
	v_mfma_f32_32x32x16_bf16 v[80:95], v[224:227], v[120:123], v[80:95]
	s_waitcnt lgkmcnt(1)
	v_mfma_f32_32x32x16_bf16 v[80:95], v[2:5], v[116:119], v[80:95]
	s_waitcnt lgkmcnt(0)
	v_mfma_f32_32x32x16_bf16 v[80:95], v[6:9], v[112:115], v[80:95]
	s_branch .LBB0_1401
.LBB0_1400:
	s_mov_b32 s100, 0
	v_mov_b32_e32 v14, v0
	v_mov_b32_e32 v15, v0
	v_mov_b32_e32 v1, v0
	v_mov_b32_e32 v2, v0
	v_mov_b32_e32 v3, v0
	v_mov_b32_e32 v4, v0
	v_mov_b32_e32 v5, v0
	v_mov_b32_e32 v6, v0
	v_mov_b32_e32 v7, v0
	v_mov_b32_e32 v8, v0
	v_mov_b32_e32 v9, v0
	v_mov_b32_e32 v10, v0
	v_mov_b32_e32 v11, v0
	v_mov_b32_e32 v12, v0
	v_mov_b32_e32 v13, v0
	v_mov_b64_e32 v[94:95], v[14:15]
	v_mov_b64_e32 v[92:93], v[12:13]
	v_mov_b64_e32 v[90:91], v[10:11]
	v_mov_b64_e32 v[88:89], v[8:9]
	v_mov_b64_e32 v[86:87], v[6:7]
	v_mov_b64_e32 v[84:85], v[4:5]
	v_mov_b64_e32 v[82:83], v[2:3]
	v_mov_b64_e32 v[80:81], v[0:1]

.LBB0_1411:
	s_cmp_lg_u32 s100, 0
	s_cbranch_scc1 .Lmq1_h0
	v_fma_f32 v3, v96, s53, -v202
	v_exp_f32_e32 v3, v3
	v_fma_f32 v4, v97, s53, -v202
	v_exp_f32_e32 v4, v4
	v_fma_f32 v5, v98, s53, -v202
	v_exp_f32_e32 v5, v5
	v_fma_f32 v6, v99, s53, -v202
	v_exp_f32_e32 v6, v6
	v_fma_f32 v8, v100, s53, -v202
	v_add_f32_e32 v7, 0, v3
	v_exp_f32_e32 v8, v8
	v_fma_f32 v9, v101, s53, -v202
	v_add_f32_e32 v7, v4, v7
	v_exp_f32_e32 v9, v9
	v_fma_f32 v10, v102, s53, -v202
	v_add_f32_e32 v7, v5, v7
	v_exp_f32_e32 v10, v10
	v_fma_f32 v11, v103, s53, -v202
	v_add_f32_e32 v7, v6, v7
	v_exp_f32_e32 v11, v11
	v_fma_f32 v12, v104, s53, -v202
	v_add_f32_e32 v7, v8, v7
	v_exp_f32_e32 v14, v12
	v_fma_f32 v12, v105, s53, -v202
	v_add_f32_e32 v7, v9, v7
	v_exp_f32_e32 v15, v12
	v_fma_f32 v12, v106, s53, -v202
	v_add_f32_e32 v7, v10, v7
	v_exp_f32_e32 v105, v12
	v_fma_f32 v12, v107, s53, -v202
	v_add_f32_e32 v7, v11, v7
	v_exp_f32_e32 v106, v12
	v_fma_f32 v12, v108, s53, -v202
	v_add_f32_e32 v7, v14, v7
	v_exp_f32_e32 v107, v12
	v_fma_f32 v12, v109, s53, -v202
	v_add_f32_e32 v7, v15, v7
	v_exp_f32_e32 v108, v12
	v_fma_f32 v12, v110, s53, -v202
	v_add_f32_e32 v7, v105, v7
	v_exp_f32_e32 v109, v12
	v_fma_f32 v12, v111, s53, -v202
	v_add_f32_e32 v7, v106, v7
	v_exp_f32_e32 v110, v12
	v_add_f32_e32 v7, v107, v7
	v_add_f32_e32 v7, v108, v7
	v_add_f32_e32 v7, v109, v7
	v_add_f32_e32 v220, v110, v7
	v_fmac_f32_e32 v220, v203, v2
.Lmq1_tail:
	v_cvt_pk_bf16_f32 v2, v3, v4
	v_cvt_pk_bf16_f32 v3, v5, v6
	v_cvt_pk_bf16_f32 v5, v10, v11
	v_add_u32_e32 v10, 0x6000, v1
	v_add_u32_e32 v100, 0x7000, v1
	v_cvt_pk_bf16_f32 v4, v8, v9
	ds_read2_b64 v[6:9], v10 offset0:128 offset1:130
	ds_read2_b64 v[10:13], v10 offset0:132 offset1:134
	ds_read2_b64 v[96:99], v100 offset0:160 offset1:162
	ds_read2_b64 v[100:103], v100 offset0:164 offset1:166
	v_cvt_pk_bf16_f32 v104, v14, v15
	v_cvt_pk_bf16_f32 v105, v105, v106
	v_cvt_pk_bf16_f32 v106, v107, v108
	v_cvt_pk_bf16_f32 v107, v109, v110
	s_waitcnt lgkmcnt(3)
	v_mfma_f32_32x32x16_bf16 v[64:79], v[6:9], v[2:5], v[64:79]
	v_add_u32_e32 v14, 0x8000, v1
	ds_read2_b64 v[108:111], v14 offset0:192 offset1:194
	s_waitcnt lgkmcnt(3)
	v_mfma_f32_32x32x16_bf16 v[64:79], v[10:13], v[104:107], v[64:79]
	ds_read2_b64 v[6:9], v14 offset0:196 offset1:198
	s_waitcnt lgkmcnt(3)
	v_mfma_f32_32x32x16_bf16 v[48:63], v[96:99], v[2:5], v[48:63]
	v_add_u32_e32 v14, 0x9000, v1
	ds_read2_b64 v[10:13], v14 offset0:224 offset1:226
	s_waitcnt lgkmcnt(3)
	v_mfma_f32_32x32x16_bf16 v[48:63], v[100:103], v[104:107], v[48:63]
	ds_read2_b64 v[96:99], v14 offset0:228 offset1:230
	s_waitcnt lgkmcnt(3)
	v_mfma_f32_32x32x16_bf16 v[32:47], v[108:111], v[2:5], v[32:47]
	s_waitcnt lgkmcnt(2)
	v_mfma_f32_32x32x16_bf16 v[32:47], v[6:9], v[104:107], v[32:47]
	s_waitcnt lgkmcnt(1)
	v_mfma_f32_32x32x16_bf16 v[16:31], v[10:13], v[2:5], v[16:31]
	s_waitcnt lgkmcnt(0)
	v_mfma_f32_32x32x16_bf16 v[16:31], v[96:99], v[104:107], v[16:31]
	v_mov_b32_e32 v203, v220
	s_andn2_b64 vcc, exec, s[0:1]
	s_cbranch_vccnz .LBB0_1392

; template <int DQK, int NMAP, int DV> ...
;     ...
;       if (act0) ATTN_QK(sa0, kbase + c * DQK);
.Lmq1_h0:
	s_waitcnt lgkmcnt(0)
	v_mfma_f32_32x32x16_bf16 v[80:95], v[228:231], v[156:159], 0
	ds_read_b128 v[244:247], v248 offset:12928
	v_fma_f32 v3, v96, s53, -v202
	v_exp_f32_e32 v3, v3
	v_fma_f32 v4, v97, s53, -v202
	v_exp_f32_e32 v4, v4
	s_waitcnt lgkmcnt(3)
	v_mfma_f32_32x32x16_bf16 v[80:95], v[232:235], v[152:155], v[80:95]
	ds_read_b128 v[228:231], v248 offset:12960
	v_fma_f32 v5, v98, s53, -v202
	v_exp_f32_e32 v5, v5
	v_fma_f32 v6, v99, s53, -v202
	v_exp_f32_e32 v6, v6
	s_waitcnt lgkmcnt(3)
	v_mfma_f32_32x32x16_bf16 v[80:95], v[236:239], v[148:151], v[80:95]
	ds_read_b128 v[232:235], v248 offset:12992
	v_fma_f32 v8, v100, s53, -v202
	v_add_f32_e32 v7, 0, v3
	v_exp_f32_e32 v8, v8
	v_fma_f32 v9, v101, s53, -v202
	s_waitcnt lgkmcnt(3)
	v_mfma_f32_32x32x16_bf16 v[80:95], v[240:243], v[144:147], v[80:95]
	ds_read_b128 v[236:239], v248 offset:13024
	v_add_f32_e32 v7, v4, v7
	v_exp_f32_e32 v9, v9
	v_fma_f32 v10, v102, s53, -v202
	v_add_f32_e32 v7, v5, v7
	s_waitcnt lgkmcnt(3)
	v_mfma_f32_32x32x16_bf16 v[80:95], v[244:247], v[140:143], v[80:95]
	ds_read_b128 v[240:243], v248 offset:13056
	v_exp_f32_e32 v10, v10
	v_fma_f32 v11, v103, s53, -v202
	v_add_f32_e32 v7, v6, v7
	v_exp_f32_e32 v11, v11
	s_waitcnt lgkmcnt(3)
	v_mfma_f32_32x32x16_bf16 v[80:95], v[228:231], v[136:139], v[80:95]
	ds_read_b128 v[244:247], v248 offset:13088
	v_fma_f32 v12, v104, s53, -v202
	v_add_f32_e32 v7, v8, v7
	v_exp_f32_e32 v14, v12
	v_fma_f32 v12, v105, s53, -v202
	s_waitcnt lgkmcnt(3)
	v_mfma_f32_32x32x16_bf16 v[80:95], v[232:235], v[132:135], v[80:95]
	ds_read_b128 v[228:231], v248 offset:13120
	v_add_f32_e32 v7, v9, v7
	v_exp_f32_e32 v15, v12
	v_fma_f32 v12, v106, s53, -v202
	v_add_f32_e32 v7, v10, v7
	s_waitcnt lgkmcnt(3)
	v_mfma_f32_32x32x16_bf16 v[80:95], v[236:239], v[128:131], v[80:95]
	ds_read_b128 v[232:235], v248 offset:13152
	v_exp_f32_e32 v105, v12
	v_fma_f32 v12, v107, s53, -v202
	v_add_f32_e32 v7, v11, v7
	v_exp_f32_e32 v106, v12
	s_waitcnt lgkmcnt(3)
	v_mfma_f32_32x32x16_bf16 v[80:95], v[240:243], v[124:127], v[80:95]
	v_fma_f32 v12, v108, s53, -v202
	v_add_f32_e32 v7, v14, v7
	v_exp_f32_e32 v107, v12
	v_fma_f32 v12, v109, s53, -v202
	s_waitcnt lgkmcnt(2)
	v_mfma_f32_32x32x16_bf16 v[80:95], v[244:247], v[120:123], v[80:95]
	v_add_f32_e32 v7, v15, v7
	v_exp_f32_e32 v108, v12
	v_fma_f32 v12, v110, s53, -v202
	v_add_f32_e32 v7, v105, v7
	s_waitcnt lgkmcnt(1)
	v_mfma_f32_32x32x16_bf16 v[80:95], v[228:231], v[116:119], v[80:95]
	v_exp_f32_e32 v109, v12
	v_fma_f32 v12, v111, s53, -v202
	v_add_f32_e32 v7, v106, v7
	v_exp_f32_e32 v110, v12
	s_waitcnt lgkmcnt(0)
	v_mfma_f32_32x32x16_bf16 v[80:95], v[232:235], v[112:115], v[80:95]
	v_add_f32_e32 v7, v107, v7
	v_add_f32_e32 v7, v108, v7
	v_add_f32_e32 v7, v109, v7
	v_add_f32_e32 v220, v110, v7
	v_fmac_f32_e32 v220, v203, v2
	s_branch .Lmq1_tail
